# E_UQ epilogue: row sum of squares keeps 12 loads in flight with rolling counted vmcnt (on top of the batched projection epilogue)
# baseline (speedup 1.0000x reference)
; DI int otid() { int t = threadIdx.x; asm volatile("" : "+v"(t)); return t; }
; DI float bf_lo(unsigned u) { return __uint_as_float(u << 16); }
; DI float bf_hi(unsigned u) { return __uint_as_float(u & 0xffff0000u); }
; DI void gemm_run(const GemmDesc& d, char* lds) {
;     ...
;             const int tq_ = otid(), r = tq_ >> 1, hf = tq_ & 1;
;             const u32x4* src = (const u32x4*)(d.A + (long)(brow + r) * 384 + hf * 192);
;             float sq = 0.f;
; #pragma unroll 4
;             for (int i = 0; i < 24; ++i) { u32x4 v = src[i];
;                 for (int e = 0; e < 4; ++e) { float a_ = bf_lo(v[e]), b_ = bf_hi(v[e]); sq += a_ * a_ + b_ * b_; } }
.LBB0_524:
	s_mul_hi_u32 s2, s12, s69
	s_mul_i32 s3, s2, s64
	s_sub_i32 s3, s12, s3
	s_add_i32 s8, s2, 1
	s_sub_i32 s9, s3, s64
	s_cmp_ge_u32 s3, s64
	s_cselect_b32 s2, s8, s2
	s_cselect_b32 s3, s9, s3
	s_add_i32 s8, s2, 1
	s_cmp_ge_u32 s3, s64
	s_cselect_b32 s8, s8, s2
	s_andn2_b64 vcc, exec, s[50:51]
	s_lshl_b32 s62, s8, 8
	s_cbranch_vccnz .LBB0_530
	v_mov_b32_e32 v128, v186
	s_nop 0
	v_ashrrev_i32_e32 v130, 1, v128
	v_and_b32_e32 v131, 1, v128
	v_add_u32_e32 v140, s62, v130
	v_mov_b64_e32 v[128:129], s[16:17]
	v_mad_i64_i32 v[128:129], s[2:3], v140, s95, v[128:129]
	v_mul_u32_u24_e32 v140, 0xc0, v131
	v_lshlrev_b32_e32 v140, 1, v140
	v_lshl_add_u64 v[128:129], v[128:129], 0, v[140:141]
	global_load_dwordx4 v[204:207], v[128:129], off
	global_load_dwordx4 v[208:211], v[128:129], off offset:16
	global_load_dwordx4 v[212:215], v[128:129], off offset:32
	global_load_dwordx4 v[216:219], v[128:129], off offset:48
	global_load_dwordx4 v[220:223], v[128:129], off offset:64
	global_load_dwordx4 v[224:227], v[128:129], off offset:80
	global_load_dwordx4 v[228:231], v[128:129], off offset:96
	global_load_dwordx4 v[232:235], v[128:129], off offset:112
	global_load_dwordx4 v[236:239], v[128:129], off offset:128
	global_load_dwordx4 v[240:243], v[128:129], off offset:144
	global_load_dwordx4 v[244:247], v[128:129], off offset:160
	global_load_dwordx4 v[146:149], v[128:129], off offset:176
	v_mov_b32_e32 v140, 0
	v_mov_b32_e32 v150, 0
	s_waitcnt vmcnt(11)
	v_lshlrev_b32_e32 v151, 16, v204
	v_and_b32_e32 v152, 0xffff0000, v204
	v_lshlrev_b32_e32 v153, 16, v205
	v_and_b32_e32 v154, 0xffff0000, v205
	v_lshlrev_b32_e32 v155, 16, v206
	v_and_b32_e32 v156, 0xffff0000, v206
	v_lshlrev_b32_e32 v157, 16, v207
	v_and_b32_e32 v158, 0xffff0000, v207
	v_fmac_f32_e32 v140, v151, v151
	v_fmac_f32_e32 v140, v152, v152
	v_fmac_f32_e32 v140, v153, v153
	v_fmac_f32_e32 v140, v154, v154
	v_fmac_f32_e32 v140, v155, v155
	v_fmac_f32_e32 v140, v156, v156
	v_fmac_f32_e32 v140, v157, v157
	v_fmac_f32_e32 v140, v158, v158
	global_load_dwordx4 v[204:207], v[128:129], off offset:192
	s_waitcnt vmcnt(11)
	v_lshlrev_b32_e32 v151, 16, v208
	v_and_b32_e32 v152, 0xffff0000, v208
	v_lshlrev_b32_e32 v153, 16, v209
	v_and_b32_e32 v154, 0xffff0000, v209
	v_lshlrev_b32_e32 v155, 16, v210
	v_and_b32_e32 v156, 0xffff0000, v210
	v_lshlrev_b32_e32 v157, 16, v211
	v_and_b32_e32 v158, 0xffff0000, v211
	v_fmac_f32_e32 v150, v151, v151
	v_fmac_f32_e32 v150, v152, v152
	v_fmac_f32_e32 v150, v153, v153
	v_fmac_f32_e32 v150, v154, v154
	v_fmac_f32_e32 v150, v155, v155
	v_fmac_f32_e32 v150, v156, v156
	v_fmac_f32_e32 v150, v157, v157
	v_fmac_f32_e32 v150, v158, v158
	global_load_dwordx4 v[208:211], v[128:129], off offset:208
	s_waitcnt vmcnt(11)
	v_lshlrev_b32_e32 v151, 16, v212
	v_and_b32_e32 v152, 0xffff0000, v212
	v_lshlrev_b32_e32 v153, 16, v213
	v_and_b32_e32 v154, 0xffff0000, v213
	v_lshlrev_b32_e32 v155, 16, v214
	v_and_b32_e32 v156, 0xffff0000, v214
	v_lshlrev_b32_e32 v157, 16, v215
	v_and_b32_e32 v158, 0xffff0000, v215
	v_fmac_f32_e32 v140, v151, v151
	v_fmac_f32_e32 v140, v152, v152
	v_fmac_f32_e32 v140, v153, v153
	v_fmac_f32_e32 v140, v154, v154
	v_fmac_f32_e32 v140, v155, v155
	v_fmac_f32_e32 v140, v156, v156
	v_fmac_f32_e32 v140, v157, v157
	v_fmac_f32_e32 v140, v158, v158
	global_load_dwordx4 v[212:215], v[128:129], off offset:224
	s_waitcnt vmcnt(11)
	v_lshlrev_b32_e32 v151, 16, v216
	v_and_b32_e32 v152, 0xffff0000, v216
	v_lshlrev_b32_e32 v153, 16, v217
	v_and_b32_e32 v154, 0xffff0000, v217
	v_lshlrev_b32_e32 v155, 16, v218
	v_and_b32_e32 v156, 0xffff0000, v218
	v_lshlrev_b32_e32 v157, 16, v219
	v_and_b32_e32 v158, 0xffff0000, v219
	v_fmac_f32_e32 v150, v151, v151
	v_fmac_f32_e32 v150, v152, v152
	v_fmac_f32_e32 v150, v153, v153
	v_fmac_f32_e32 v150, v154, v154
	v_fmac_f32_e32 v150, v155, v155
	v_fmac_f32_e32 v150, v156, v156
	v_fmac_f32_e32 v150, v157, v157
	v_fmac_f32_e32 v150, v158, v158
	global_load_dwordx4 v[216:219], v[128:129], off offset:240
	s_waitcnt vmcnt(11)
	v_lshlrev_b32_e32 v151, 16, v220
	v_and_b32_e32 v152, 0xffff0000, v220
	v_lshlrev_b32_e32 v153, 16, v221
	v_and_b32_e32 v154, 0xffff0000, v221
	v_lshlrev_b32_e32 v155, 16, v222
	v_and_b32_e32 v156, 0xffff0000, v222
	v_lshlrev_b32_e32 v157, 16, v223
	v_and_b32_e32 v158, 0xffff0000, v223
	v_fmac_f32_e32 v140, v151, v151
	v_fmac_f32_e32 v140, v152, v152
	v_fmac_f32_e32 v140, v153, v153
	v_fmac_f32_e32 v140, v154, v154
	v_fmac_f32_e32 v140, v155, v155
	v_fmac_f32_e32 v140, v156, v156
	v_fmac_f32_e32 v140, v157, v157
	v_fmac_f32_e32 v140, v158, v158
	global_load_dwordx4 v[220:223], v[128:129], off offset:256
	s_waitcnt vmcnt(11)
	v_lshlrev_b32_e32 v151, 16, v224
	v_and_b32_e32 v152, 0xffff0000, v224
	v_lshlrev_b32_e32 v153, 16, v225
	v_and_b32_e32 v154, 0xffff0000, v225
	v_lshlrev_b32_e32 v155, 16, v226
	v_and_b32_e32 v156, 0xffff0000, v226
	v_lshlrev_b32_e32 v157, 16, v227
	v_and_b32_e32 v158, 0xffff0000, v227
	v_fmac_f32_e32 v150, v151, v151
	v_fmac_f32_e32 v150, v152, v152
	v_fmac_f32_e32 v150, v153, v153
	v_fmac_f32_e32 v150, v154, v154
	v_fmac_f32_e32 v150, v155, v155
	v_fmac_f32_e32 v150, v156, v156
	v_fmac_f32_e32 v150, v157, v157
	v_fmac_f32_e32 v150, v158, v158
	global_load_dwordx4 v[224:227], v[128:129], off offset:272
	s_waitcnt vmcnt(11)
	v_lshlrev_b32_e32 v151, 16, v228
	v_and_b32_e32 v152, 0xffff0000, v228
	v_lshlrev_b32_e32 v153, 16, v229
	v_and_b32_e32 v154, 0xffff0000, v229
	v_lshlrev_b32_e32 v155, 16, v230
	v_and_b32_e32 v156, 0xffff0000, v230
	v_lshlrev_b32_e32 v157, 16, v231
	v_and_b32_e32 v158, 0xffff0000, v231
	v_fmac_f32_e32 v140, v151, v151
	v_fmac_f32_e32 v140, v152, v152
	v_fmac_f32_e32 v140, v153, v153
	v_fmac_f32_e32 v140, v154, v154
	v_fmac_f32_e32 v140, v155, v155
	v_fmac_f32_e32 v140, v156, v156
	v_fmac_f32_e32 v140, v157, v157
	v_fmac_f32_e32 v140, v158, v158
	global_load_dwordx4 v[228:231], v[128:129], off offset:288
	s_waitcnt vmcnt(11)
; DI int otid() { int t = threadIdx.x; asm volatile("" : "+v"(t)); return t; }
; DI float bf_lo(unsigned u) { return __uint_as_float(u << 16); }
; DI float bf_hi(unsigned u) { return __uint_as_float(u & 0xffff0000u); }
; DI void gemm_run(const GemmDesc& d, char* lds) {
;     ...
;             const int tq_ = otid(), r = tq_ >> 1, hf = tq_ & 1;
;             const u32x4* src = (const u32x4*)(d.A + (long)(brow + r) * 384 + hf * 192);
;             float sq = 0.f;
; #pragma unroll 4
;             for (int i = 0; i < 24; ++i) { u32x4 v = src[i];
;                 for (int e = 0; e < 4; ++e) { float a_ = bf_lo(v[e]), b_ = bf_hi(v[e]); sq += a_ * a_ + b_ * b_; } }
	v_lshlrev_b32_e32 v151, 16, v232
	v_and_b32_e32 v152, 0xffff0000, v232
	v_lshlrev_b32_e32 v153, 16, v233
	v_and_b32_e32 v154, 0xffff0000, v233
	v_lshlrev_b32_e32 v155, 16, v234
	v_and_b32_e32 v156, 0xffff0000, v234
	v_lshlrev_b32_e32 v157, 16, v235
	v_and_b32_e32 v158, 0xffff0000, v235
	v_fmac_f32_e32 v150, v151, v151
	v_fmac_f32_e32 v150, v152, v152
	v_fmac_f32_e32 v150, v153, v153
	v_fmac_f32_e32 v150, v154, v154
	v_fmac_f32_e32 v150, v155, v155
	v_fmac_f32_e32 v150, v156, v156
	v_fmac_f32_e32 v150, v157, v157
	v_fmac_f32_e32 v150, v158, v158
	global_load_dwordx4 v[232:235], v[128:129], off offset:304
	s_waitcnt vmcnt(11)
	v_lshlrev_b32_e32 v151, 16, v236
	v_and_b32_e32 v152, 0xffff0000, v236
	v_lshlrev_b32_e32 v153, 16, v237
	v_and_b32_e32 v154, 0xffff0000, v237
	v_lshlrev_b32_e32 v155, 16, v238
	v_and_b32_e32 v156, 0xffff0000, v238
	v_lshlrev_b32_e32 v157, 16, v239
	v_and_b32_e32 v158, 0xffff0000, v239
	v_fmac_f32_e32 v140, v151, v151
	v_fmac_f32_e32 v140, v152, v152
	v_fmac_f32_e32 v140, v153, v153
	v_fmac_f32_e32 v140, v154, v154
	v_fmac_f32_e32 v140, v155, v155
	v_fmac_f32_e32 v140, v156, v156
	v_fmac_f32_e32 v140, v157, v157
	v_fmac_f32_e32 v140, v158, v158
	global_load_dwordx4 v[236:239], v[128:129], off offset:320
	s_waitcnt vmcnt(11)
	v_lshlrev_b32_e32 v151, 16, v240
	v_and_b32_e32 v152, 0xffff0000, v240
	v_lshlrev_b32_e32 v153, 16, v241
	v_and_b32_e32 v154, 0xffff0000, v241
	v_lshlrev_b32_e32 v155, 16, v242
	v_and_b32_e32 v156, 0xffff0000, v242
	v_lshlrev_b32_e32 v157, 16, v243
	v_and_b32_e32 v158, 0xffff0000, v243
	v_fmac_f32_e32 v150, v151, v151
	v_fmac_f32_e32 v150, v152, v152
	v_fmac_f32_e32 v150, v153, v153
	v_fmac_f32_e32 v150, v154, v154
	v_fmac_f32_e32 v150, v155, v155
	v_fmac_f32_e32 v150, v156, v156
	v_fmac_f32_e32 v150, v157, v157
	v_fmac_f32_e32 v150, v158, v158
	global_load_dwordx4 v[240:243], v[128:129], off offset:336
	s_waitcnt vmcnt(11)
	v_lshlrev_b32_e32 v151, 16, v244
	v_and_b32_e32 v152, 0xffff0000, v244
	v_lshlrev_b32_e32 v153, 16, v245
	v_and_b32_e32 v154, 0xffff0000, v245
	v_lshlrev_b32_e32 v155, 16, v246
	v_and_b32_e32 v156, 0xffff0000, v246
	v_lshlrev_b32_e32 v157, 16, v247
	v_and_b32_e32 v158, 0xffff0000, v247
	v_fmac_f32_e32 v140, v151, v151
	v_fmac_f32_e32 v140, v152, v152
	v_fmac_f32_e32 v140, v153, v153
	v_fmac_f32_e32 v140, v154, v154
	v_fmac_f32_e32 v140, v155, v155
	v_fmac_f32_e32 v140, v156, v156
	v_fmac_f32_e32 v140, v157, v157
	v_fmac_f32_e32 v140, v158, v158
	global_load_dwordx4 v[244:247], v[128:129], off offset:352
	s_waitcnt vmcnt(11)
	v_lshlrev_b32_e32 v151, 16, v146
	v_and_b32_e32 v152, 0xffff0000, v146
	v_lshlrev_b32_e32 v153, 16, v147
	v_and_b32_e32 v154, 0xffff0000, v147
	v_lshlrev_b32_e32 v155, 16, v148
	v_and_b32_e32 v156, 0xffff0000, v148
	v_lshlrev_b32_e32 v157, 16, v149
	v_and_b32_e32 v158, 0xffff0000, v149
	v_fmac_f32_e32 v150, v151, v151
	v_fmac_f32_e32 v150, v152, v152
	v_fmac_f32_e32 v150, v153, v153
	v_fmac_f32_e32 v150, v154, v154
	v_fmac_f32_e32 v150, v155, v155
	v_fmac_f32_e32 v150, v156, v156
	v_fmac_f32_e32 v150, v157, v157
	v_fmac_f32_e32 v150, v158, v158
	global_load_dwordx4 v[146:149], v[128:129], off offset:368
	s_waitcnt vmcnt(11)
	v_lshlrev_b32_e32 v151, 16, v204
	v_and_b32_e32 v152, 0xffff0000, v204
	v_lshlrev_b32_e32 v153, 16, v205
	v_and_b32_e32 v154, 0xffff0000, v205
	v_lshlrev_b32_e32 v155, 16, v206
	v_and_b32_e32 v156, 0xffff0000, v206
	v_lshlrev_b32_e32 v157, 16, v207
	v_and_b32_e32 v158, 0xffff0000, v207
	v_fmac_f32_e32 v140, v151, v151
	v_fmac_f32_e32 v140, v152, v152
	v_fmac_f32_e32 v140, v153, v153
	v_fmac_f32_e32 v140, v154, v154
	v_fmac_f32_e32 v140, v155, v155
	v_fmac_f32_e32 v140, v156, v156
	v_fmac_f32_e32 v140, v157, v157
	v_fmac_f32_e32 v140, v158, v158
	s_waitcnt vmcnt(10)
	v_lshlrev_b32_e32 v151, 16, v208
	v_and_b32_e32 v152, 0xffff0000, v208
	v_lshlrev_b32_e32 v153, 16, v209
	v_and_b32_e32 v154, 0xffff0000, v209
	v_lshlrev_b32_e32 v155, 16, v210
	v_and_b32_e32 v156, 0xffff0000, v210
	v_lshlrev_b32_e32 v157, 16, v211
	v_and_b32_e32 v158, 0xffff0000, v211
	v_fmac_f32_e32 v150, v151, v151
	v_fmac_f32_e32 v150, v152, v152
	v_fmac_f32_e32 v150, v153, v153
	v_fmac_f32_e32 v150, v154, v154
	v_fmac_f32_e32 v150, v155, v155
	v_fmac_f32_e32 v150, v156, v156
	v_fmac_f32_e32 v150, v157, v157
	v_fmac_f32_e32 v150, v158, v158
	s_waitcnt vmcnt(9)
	v_lshlrev_b32_e32 v151, 16, v212
	v_and_b32_e32 v152, 0xffff0000, v212
	v_lshlrev_b32_e32 v153, 16, v213
	v_and_b32_e32 v154, 0xffff0000, v213
	v_lshlrev_b32_e32 v155, 16, v214
	v_and_b32_e32 v156, 0xffff0000, v214
	v_lshlrev_b32_e32 v157, 16, v215
	v_and_b32_e32 v158, 0xffff0000, v215
	v_fmac_f32_e32 v140, v151, v151
	v_fmac_f32_e32 v140, v152, v152
	v_fmac_f32_e32 v140, v153, v153
	v_fmac_f32_e32 v140, v154, v154
	v_fmac_f32_e32 v140, v155, v155
	v_fmac_f32_e32 v140, v156, v156
	v_fmac_f32_e32 v140, v157, v157
	v_fmac_f32_e32 v140, v158, v158
	s_waitcnt vmcnt(8)
	v_lshlrev_b32_e32 v151, 16, v216
	v_and_b32_e32 v152, 0xffff0000, v216
	v_lshlrev_b32_e32 v153, 16, v217
	v_and_b32_e32 v154, 0xffff0000, v217
	v_lshlrev_b32_e32 v155, 16, v218
	v_and_b32_e32 v156, 0xffff0000, v218
	v_lshlrev_b32_e32 v157, 16, v219
	v_and_b32_e32 v158, 0xffff0000, v219
	v_fmac_f32_e32 v150, v151, v151
	v_fmac_f32_e32 v150, v152, v152
	v_fmac_f32_e32 v150, v153, v153
	v_fmac_f32_e32 v150, v154, v154
	v_fmac_f32_e32 v150, v155, v155
	v_fmac_f32_e32 v150, v156, v156
	v_fmac_f32_e32 v150, v157, v157
	v_fmac_f32_e32 v150, v158, v158
	s_waitcnt vmcnt(7)
; DI int otid() { int t = threadIdx.x; asm volatile("" : "+v"(t)); return t; }
; DI float bf_lo(unsigned u) { return __uint_as_float(u << 16); }
; DI float bf_hi(unsigned u) { return __uint_as_float(u & 0xffff0000u); }
; #define WAIT_L(n) asm volatile("s_waitcnt lgkmcnt(" #n ")" ::: "memory")
; #define BAR __builtin_amdgcn_s_barrier()
; DI void gemm_run(const GemmDesc& d, char* lds) {
;     ...
;             const int tq_ = otid(), r = tq_ >> 1, hf = tq_ & 1;
;             const u32x4* src = (const u32x4*)(d.A + (long)(brow + r) * 384 + hf * 192);
;             float sq = 0.f;
; #pragma unroll 4
;             for (int i = 0; i < 24; ++i) { u32x4 v = src[i];
;                 for (int e = 0; e < 4; ++e) { float a_ = bf_lo(v[e]), b_ = bf_hi(v[e]); sq += a_ * a_ + b_ * b_; } }
;             sq += __shfl_xor(sq, 1);
;             if (hf == 0) xl[r] = rsqrtf(sq * (1.0f / 384.0f) + EPS);
;             WAIT_L(0); BAR; asm volatile("" ::: "memory");
	v_lshlrev_b32_e32 v151, 16, v220
	v_and_b32_e32 v152, 0xffff0000, v220
	v_lshlrev_b32_e32 v153, 16, v221
	v_and_b32_e32 v154, 0xffff0000, v221
	v_lshlrev_b32_e32 v155, 16, v222
	v_and_b32_e32 v156, 0xffff0000, v222
	v_lshlrev_b32_e32 v157, 16, v223
	v_and_b32_e32 v158, 0xffff0000, v223
	v_fmac_f32_e32 v140, v151, v151
	v_fmac_f32_e32 v140, v152, v152
	v_fmac_f32_e32 v140, v153, v153
	v_fmac_f32_e32 v140, v154, v154
	v_fmac_f32_e32 v140, v155, v155
	v_fmac_f32_e32 v140, v156, v156
	v_fmac_f32_e32 v140, v157, v157
	v_fmac_f32_e32 v140, v158, v158
	s_waitcnt vmcnt(6)
	v_lshlrev_b32_e32 v151, 16, v224
	v_and_b32_e32 v152, 0xffff0000, v224
	v_lshlrev_b32_e32 v153, 16, v225
	v_and_b32_e32 v154, 0xffff0000, v225
	v_lshlrev_b32_e32 v155, 16, v226
	v_and_b32_e32 v156, 0xffff0000, v226
	v_lshlrev_b32_e32 v157, 16, v227
	v_and_b32_e32 v158, 0xffff0000, v227
	v_fmac_f32_e32 v150, v151, v151
	v_fmac_f32_e32 v150, v152, v152
	v_fmac_f32_e32 v150, v153, v153
	v_fmac_f32_e32 v150, v154, v154
	v_fmac_f32_e32 v150, v155, v155
	v_fmac_f32_e32 v150, v156, v156
	v_fmac_f32_e32 v150, v157, v157
	v_fmac_f32_e32 v150, v158, v158
	s_waitcnt vmcnt(5)
	v_lshlrev_b32_e32 v151, 16, v228
	v_and_b32_e32 v152, 0xffff0000, v228
	v_lshlrev_b32_e32 v153, 16, v229
	v_and_b32_e32 v154, 0xffff0000, v229
	v_lshlrev_b32_e32 v155, 16, v230
	v_and_b32_e32 v156, 0xffff0000, v230
	v_lshlrev_b32_e32 v157, 16, v231
	v_and_b32_e32 v158, 0xffff0000, v231
	v_fmac_f32_e32 v140, v151, v151
	v_fmac_f32_e32 v140, v152, v152
	v_fmac_f32_e32 v140, v153, v153
	v_fmac_f32_e32 v140, v154, v154
	v_fmac_f32_e32 v140, v155, v155
	v_fmac_f32_e32 v140, v156, v156
	v_fmac_f32_e32 v140, v157, v157
	v_fmac_f32_e32 v140, v158, v158
	s_waitcnt vmcnt(4)
	v_lshlrev_b32_e32 v151, 16, v232
	v_and_b32_e32 v152, 0xffff0000, v232
	v_lshlrev_b32_e32 v153, 16, v233
	v_and_b32_e32 v154, 0xffff0000, v233
	v_lshlrev_b32_e32 v155, 16, v234
	v_and_b32_e32 v156, 0xffff0000, v234
	v_lshlrev_b32_e32 v157, 16, v235
	v_and_b32_e32 v158, 0xffff0000, v235
	v_fmac_f32_e32 v150, v151, v151
	v_fmac_f32_e32 v150, v152, v152
	v_fmac_f32_e32 v150, v153, v153
	v_fmac_f32_e32 v150, v154, v154
	v_fmac_f32_e32 v150, v155, v155
	v_fmac_f32_e32 v150, v156, v156
	v_fmac_f32_e32 v150, v157, v157
	v_fmac_f32_e32 v150, v158, v158
	s_waitcnt vmcnt(3)
	v_lshlrev_b32_e32 v151, 16, v236
	v_and_b32_e32 v152, 0xffff0000, v236
	v_lshlrev_b32_e32 v153, 16, v237
	v_and_b32_e32 v154, 0xffff0000, v237
	v_lshlrev_b32_e32 v155, 16, v238
	v_and_b32_e32 v156, 0xffff0000, v238
	v_lshlrev_b32_e32 v157, 16, v239
	v_and_b32_e32 v158, 0xffff0000, v239
	v_fmac_f32_e32 v140, v151, v151
	v_fmac_f32_e32 v140, v152, v152
	v_fmac_f32_e32 v140, v153, v153
	v_fmac_f32_e32 v140, v154, v154
	v_fmac_f32_e32 v140, v155, v155
	v_fmac_f32_e32 v140, v156, v156
	v_fmac_f32_e32 v140, v157, v157
	v_fmac_f32_e32 v140, v158, v158
	s_waitcnt vmcnt(2)
	v_lshlrev_b32_e32 v151, 16, v240
	v_and_b32_e32 v152, 0xffff0000, v240
	v_lshlrev_b32_e32 v153, 16, v241
	v_and_b32_e32 v154, 0xffff0000, v241
	v_lshlrev_b32_e32 v155, 16, v242
	v_and_b32_e32 v156, 0xffff0000, v242
	v_lshlrev_b32_e32 v157, 16, v243
	v_and_b32_e32 v158, 0xffff0000, v243
	v_fmac_f32_e32 v150, v151, v151
	v_fmac_f32_e32 v150, v152, v152
	v_fmac_f32_e32 v150, v153, v153
	v_fmac_f32_e32 v150, v154, v154
	v_fmac_f32_e32 v150, v155, v155
	v_fmac_f32_e32 v150, v156, v156
	v_fmac_f32_e32 v150, v157, v157
	v_fmac_f32_e32 v150, v158, v158
	s_waitcnt vmcnt(1)
	v_lshlrev_b32_e32 v151, 16, v244
	v_and_b32_e32 v152, 0xffff0000, v244
	v_lshlrev_b32_e32 v153, 16, v245
	v_and_b32_e32 v154, 0xffff0000, v245
	v_lshlrev_b32_e32 v155, 16, v246
	v_and_b32_e32 v156, 0xffff0000, v246
	v_lshlrev_b32_e32 v157, 16, v247
	v_and_b32_e32 v158, 0xffff0000, v247
	v_fmac_f32_e32 v140, v151, v151
	v_fmac_f32_e32 v140, v152, v152
	v_fmac_f32_e32 v140, v153, v153
	v_fmac_f32_e32 v140, v154, v154
	v_fmac_f32_e32 v140, v155, v155
	v_fmac_f32_e32 v140, v156, v156
	v_fmac_f32_e32 v140, v157, v157
	v_fmac_f32_e32 v140, v158, v158
	s_waitcnt vmcnt(0)
	v_lshlrev_b32_e32 v151, 16, v146
	v_and_b32_e32 v152, 0xffff0000, v146
	v_lshlrev_b32_e32 v153, 16, v147
	v_and_b32_e32 v154, 0xffff0000, v147
	v_lshlrev_b32_e32 v155, 16, v148
	v_and_b32_e32 v156, 0xffff0000, v148
	v_lshlrev_b32_e32 v157, 16, v149
	v_and_b32_e32 v158, 0xffff0000, v149
	v_fmac_f32_e32 v150, v151, v151
	v_fmac_f32_e32 v150, v152, v152
	v_fmac_f32_e32 v150, v153, v153
	v_fmac_f32_e32 v150, v154, v154
	v_fmac_f32_e32 v150, v155, v155
	v_fmac_f32_e32 v150, v156, v156
	v_fmac_f32_e32 v150, v157, v157
	v_fmac_f32_e32 v150, v158, v158
	v_add_f32_e32 v140, v140, v150
	v_cmp_lt_i32_e32 vcc, v185, v184
	s_nop 1
	v_cndmask_b32_e32 v128, v183, v185, vcc
	v_lshlrev_b32_e32 v128, 2, v128
	ds_bpermute_b32 v128, v128, v140
	v_cmp_eq_u32_e32 vcc, 0, v131
	s_and_saveexec_b64 s[2:3], vcc
	s_cbranch_execz .LBB0_529
	s_waitcnt lgkmcnt(0)
	v_add_f32_e32 v128, v140, v128
	v_fmamk_f32 v128, v128, 0x3b2aaaab, v177
	v_mul_f32_e32 v129, 0x4b800000, v128
	v_cmp_gt_f32_e32 vcc, s46, v128
	s_nop 1
	v_cndmask_b32_e32 v128, v128, v129, vcc
	v_rsq_f32_e32 v128, v128
	v_lshl_add_u32 v129, v130, 2, 0
	v_add_u32_e32 v129, 0x20000, v129
	v_mul_f32_e32 v130, 0x45800000, v128
	v_cndmask_b32_e32 v128, v128, v130, vcc
	ds_write_b32 v129, v128
